# scan: staging waves raise their priority while issuing the LDS-DMA for the next chunk; gates inputs prefetched with the conv rows
# speedup vs baseline: 1.0176x; 1.0080x over previous
.LBB0_159:
	s_and_b64 vcc, exec, s[4:5]
	s_cbranch_vccz .Lscan_nostage
	s_setprio 3
	s_xor_b32 s6, s11, 1
	s_mul_i32 s6, s6, 0x12000
	v_lshl_add_u64 v[2:3], s[2:3], 0, v[52:53]
	s_mov_b64 s[12:13], 0x17c04000
	s_add_i32 s6, s6, s8
	v_lshl_add_u64 v[62:63], v[2:3], 0, s[12:13]
	s_add_i32 s6, s6, 0
	s_mov_b32 s7, m0
	s_mov_b32 m0, s6
	s_nop 0
	global_load_lds_dwordx4 v[62:63], off
	s_mov_b32 m0, s7
	v_lshl_add_u64 v[62:63], s[2:3], 0, v[50:51]
	v_lshl_add_u64 v[64:65], v[62:63], 0, s[12:13]
	s_add_i32 s7, s6, 0x2000
	s_mov_b32 s12, m0
	s_mov_b32 m0, s7
	s_nop 0
	global_load_lds_dwordx4 v[64:65], off
	s_mov_b32 m0, s12
	s_mov_b64 s[14:15], 0x15c04000
	v_lshl_add_u64 v[2:3], v[2:3], 0, s[14:15]
	s_add_i32 s7, s6, 0x4000
	s_mov_b32 s12, m0
	s_mov_b32 m0, s7
	s_nop 0
	global_load_lds_dwordx4 v[2:3], off
	s_mov_b32 m0, s12
	v_lshl_add_u64 v[2:3], v[62:63], 0, s[14:15]
	s_add_i32 s7, s6, 0x6000
	s_mov_b32 s12, m0
	s_mov_b32 m0, s7
	s_nop 0
	global_load_lds_dwordx4 v[2:3], off
	s_mov_b32 m0, s12
	v_lshl_add_u64 v[2:3], s[2:3], 0, v[48:49]
	s_add_i32 s7, s6, 0x8000
	s_mov_b32 s12, m0
	s_mov_b32 m0, s7
	s_nop 0
	global_load_lds_dwordx4 v[2:3], off
	s_mov_b32 m0, s12
	v_lshl_add_u64 v[2:3], s[2:3], 0, v[46:47]
	s_add_i32 s7, s6, 0xa000
	s_mov_b32 s12, m0
	s_mov_b32 m0, s7
	s_nop 0
	global_load_lds_dwordx4 v[2:3], off
	s_mov_b32 m0, s12
	v_lshl_add_u64 v[2:3], s[2:3], 0, v[44:45]
	s_add_i32 s7, s6, 0xc000
	s_mov_b32 s12, m0
	s_mov_b32 m0, s7
	s_nop 0
	global_load_lds_dwordx4 v[2:3], off
	s_mov_b32 m0, s12
	v_lshl_add_u64 v[2:3], s[2:3], 0, v[42:43]
	s_add_i32 s7, s6, 0xe000
	s_mov_b32 s12, m0
	s_mov_b32 m0, s7
	s_nop 0
	global_load_lds_dwordx4 v[2:3], off
	s_mov_b32 m0, s12
	v_lshl_add_u64 v[2:3], s[2:3], 0, v[40:41]
	s_add_i32 s6, s6, 0x10000
	s_mov_b32 s7, m0
	s_mov_b32 m0, s6
	s_nop 0
	global_load_lds_dwordx4 v[2:3], off
	s_mov_b32 m0, s7
	s_mov_b32 s7, m0
	s_xor_b32 s6, s11, 1
	s_mul_i32 s6, s6, 0x12000
	s_add_i32 s6, s6, s8
	s_addk_i32 s6, 0xf000
	s_add_u32 s12, s2, 0xfffff000
	s_addc_u32 s13, s3, -1
	s_mov_b64 s[14:15], 0x17c04000
	v_lshl_add_u64 v[2:3], s[12:13], 0, v[52:53]
	v_lshl_add_u64 v[64:65], s[12:13], 0, v[50:51]
	v_lshl_add_u64 v[62:63], v[2:3], 0, s[14:15]
	s_mov_b32 m0, s6
	s_nop 0
	global_load_lds_dwordx4 v[62:63], off
	v_lshl_add_u64 v[62:63], v[64:65], 0, s[14:15]
	s_add_i32 m0, s6, 0x2000
	s_mov_b64 s[14:15], 0x15c04000
	global_load_lds_dwordx4 v[62:63], off
	v_lshl_add_u64 v[62:63], v[2:3], 0, s[14:15]
	s_add_i32 m0, s6, 0x4000
	s_nop 0
	global_load_lds_dwordx4 v[62:63], off
	v_lshl_add_u64 v[62:63], v[64:65], 0, s[14:15]
	s_add_i32 m0, s6, 0x6000
	s_nop 0
	global_load_lds_dwordx4 v[62:63], off
	v_lshl_add_u64 v[2:3], s[12:13], 0, v[48:49]
	s_add_i32 m0, s6, 0x8000
	s_nop 0
	global_load_lds_dwordx4 v[2:3], off
	v_lshl_add_u64 v[2:3], s[12:13], 0, v[46:47]
	s_add_i32 m0, s6, 0xa000
	s_nop 0
	global_load_lds_dwordx4 v[2:3], off
	v_lshl_add_u64 v[2:3], s[12:13], 0, v[44:45]
	s_add_i32 m0, s6, 0xc000
	s_nop 0
	global_load_lds_dwordx4 v[2:3], off
	s_add_u32 s12, s12, 0xfffff000
	s_addc_u32 s13, s13, -1
	v_lshl_add_u64 v[2:3], s[12:13], 0, v[42:43]
	s_add_i32 m0, s6, 0xe000
	s_nop 0
	global_load_lds_dwordx4 v[2:3], off
	v_lshl_add_u64 v[2:3], s[12:13], 0, v[40:41]
	s_add_i32 m0, s6, 0x10000
	s_nop 0
	global_load_lds_dwordx4 v[2:3], off
	s_mov_b32 m0, s7
	s_setprio 0

.Lcvi_v_f:
	s_lshr_b32 s28, s88, 5
	v_lshrrev_b32_e32 v3, 4, v160
	s_sub_u32 s29, s28, 4
	s_lshl_b32 s29, s29, 4
	v_lshl_add_u32 v4, v3, 2, s29
	s_movk_i32 s99, 0x400
	s_bfe_u32 s28, s98, 0x20006
	s_lshl_b32 s28, s28, 7
	s_add_u32 s99, s99, s28
	v_and_b32_e32 v2, 15, v160
	v_lshl_add_u32 v5, v2, 3, s99
	v_lshlrev_b32_e32 v16, 2, v5
	v_add_u32_e32 v24, 0x1800, v16
	v_add_u32_e32 v34, 0x3000, v16
	v_add_u32_e32 v42, 0x4800, v16
	s_lshr_b32 s28, s98, 8
	s_lshl_b32 s28, s28, 12
	s_lshl_b32 s29, s98, 6
	s_and_b32 s29, s29, 0xfc0
	s_or_b32 s28, s28, s29
	s_sub_u32 s28, s28, 3
	v_add_u32_e32 v3, s28, v4
	v_lshlrev_b32_e32 v5, 1, v5
	v_add_u32_e32 v5, 0x800, v5
	v_mad_i32_i24 v50, v3, s76, v5
	v_add_u32_e32 v54, 0x1800, v50
	v_add_u32_e32 v58, 0x3000, v50
	v_add_u32_e32 v62, 0x4800, v50
	v_add_u32_e32 v66, 0x6000, v50
	v_add_u32_e32 v70, 0x7800, v50
	v_add_u32_e32 v74, 0x9000, v50
	v_max_i32_e32 v50, 0, v50
	v_max_i32_e32 v54, 0, v54
	v_max_i32_e32 v58, 0, v58
	global_load_dwordx4 v[20:23], v16, s[72:73] offset:16
	global_load_dwordx4 v[16:19], v16, s[72:73]
	global_load_dwordx4 v[30:33], v24, s[72:73] offset:16
	global_load_dwordx4 v[24:27], v24, s[72:73]
	global_load_dwordx4 v[38:41], v34, s[72:73] offset:16
	global_load_dwordx4 v[34:37], v34, s[72:73]
	global_load_dwordx4 v[46:49], v42, s[72:73] offset:16
	global_load_dwordx4 v[42:45], v42, s[72:73]
	global_load_dwordx4 v[50:53], v50, s[70:71]
	global_load_dwordx4 v[54:57], v54, s[70:71]
	global_load_dwordx4 v[58:61], v58, s[70:71]
	global_load_dwordx4 v[62:65], v62, s[70:71]
	global_load_dwordx4 v[66:69], v66, s[70:71]
	global_load_dwordx4 v[70:73], v70, s[70:71]
	global_load_dwordx4 v[74:77], v74, s[70:71]
	s_cmp_eq_u32 s88, 0xe0
	s_cbranch_scc0 .Lcvi_nog_f
	s_add_u32 s28, s28, 3
	v_add_u32_e32 v2, s28, v160
	s_bfe_u32 s99, s98, 0x20006
	s_lshl_b32 s28, s99, 2
	v_lshlrev_b32_e32 v2, 5, v2
	v_add_u32_e32 v2, s28, v2
	v_readlane_b32 s28, v254, 56
	v_readlane_b32 s29, v254, 57
	s_nop 4
	global_load_dword v92, v2, s[28:29]
	global_load_dword v93, v2, s[28:29] offset:16
	v_readlane_b32 s28, v254, 60
	s_nop 4
	s_add_u32 s99, s99, s28
	s_lshl_b32 s99, s99, 2
	v_mov_b32_e32 v3, s99
	v_readlane_b32 s28, v253, 50
	v_readlane_b32 s29, v253, 51
	s_nop 4
	global_load_dword v94, v3, s[28:29]
	v_readlane_b32 s28, v253, 48
	v_readlane_b32 s29, v253, 49
	s_nop 4
	global_load_dword v95, v3, s[28:29]
.Lcvi_nog_f:
.Lcvi_done_f:
	s_waitcnt vmcnt(0)
	s_branch .LBB0_175

.Lcvi_nog_n:
.Lcvi_done_n:
	v_lshl_add_u32 v10, v183, 2, v238
	s_waitcnt lgkmcnt(0)
	s_barrier
	v_add_u32_e32 v2, v10, v227
	ds_read_b128 v[2:5], v2
	s_lshl_b64 s[28:29], s[64:65], 15
	v_lshl_add_u64 v[6:7], v[84:85], 0, s[28:29]
	v_lshl_add_u64 v[8:9], v[6:7], 0, v[138:139]
	v_add3_u32 v12, v28, v236, v237
	s_waitcnt lgkmcnt(0)
	flat_store_dwordx4 v[8:9], v[2:5]
	v_lshl_add_u64 v[8:9], v[6:7], 0, v[140:141]
	s_add_i32 s64, s64, s36
	v_add_u32_e32 v2, v10, v228
	ds_read_b128 v[2:5], v2
	s_cmpk_gt_i32 s64, 0x7ff
	s_movk_i32 s65, 0xb800
	s_waitcnt lgkmcnt(0)
	flat_store_dwordx4 v[8:9], v[2:5]
	s_nop 1
	v_add_u32_e32 v2, v10, v229
	ds_read_b128 v[2:5], v2
	v_lshl_add_u64 v[8:9], v[6:7], 0, v[142:143]
	v_lshl_add_u64 v[6:7], v[6:7], 0, v[144:145]
	s_waitcnt lgkmcnt(0)
	flat_store_dwordx4 v[8:9], v[2:5]
	s_nop 1
	v_add_u32_e32 v2, v10, v230
	ds_read_b128 v[2:5], v2
	v_lshl_add_u64 v[10:11], v[86:87], 0, s[0:1]
	v_readlane_b32 s0, v255, 49
	v_readlane_b32 s1, v255, 50
	s_waitcnt lgkmcnt(0)
	flat_store_dwordx4 v[6:7], v[2:5]
	v_add_u32_e32 v6, v12, v184
	ds_read_b128 v[2:5], v6
	ds_read_b128 v[6:9], v6 offset:64
	v_lshl_add_u64 v[122:123], v[122:123], 0, s[0:1]
	s_waitcnt lgkmcnt(0)
	v_cvt_pk_bf16_f32 v2, v2, v3
	v_cvt_pk_bf16_f32 v3, v4, v5
	v_cvt_pk_bf16_f32 v4, v6, v7
	v_cvt_pk_bf16_f32 v5, v8, v9
	v_lshl_add_u64 v[6:7], v[10:11], 0, v[162:163]
	flat_store_dwordx4 v[6:7], v[2:5]
	v_add_u32_e32 v6, v12, v231
	ds_read_b128 v[2:5], v6
	ds_read_b128 v[6:9], v6 offset:64
	s_waitcnt lgkmcnt(0)
	v_cvt_pk_bf16_f32 v2, v2, v3
	v_cvt_pk_bf16_f32 v3, v4, v5
	v_cvt_pk_bf16_f32 v4, v6, v7
	v_cvt_pk_bf16_f32 v5, v8, v9
	v_lshl_add_u64 v[6:7], v[10:11], 0, v[164:165]
	flat_store_dwordx4 v[6:7], v[2:5]
	s_waitcnt lgkmcnt(0)
	s_barrier
	s_cbranch_scc1 .LBB0_342
.LBB0_175:
	s_ashr_i32 s0, s64, 8
	s_lshl_b32 s1, s64, 6
	s_and_b32 s37, s1, 0xfc0
	s_ashr_i32 s1, s0, 31
	s_lshl_b64 s[30:31], s[0:1], 12
	s_bfe_u32 s68, s64, 0x20006
	v_add_u32_e32 v239, 0x21400, v234
	s_or_b32 s30, s30, s37
	s_and_saveexec_b64 s[0:1], s[38:39]
	s_xor_b64 s[0:1], exec, s[0:1]
	s_cbranch_execz .LBB0_178
	s_andn2_b64 vcc, exec, s[14:15]
	s_cbranch_vccnz .LBB0_178
	v_mov_b32_e32 v3, s31
	v_or_b32_e32 v2, s30, v160
	v_readlane_b32 s12, v254, 56
	v_lshlrev_b64 v[2:3], 5, v[2:3]
	v_readlane_b32 s13, v254, 57
	s_ashr_i32 s69, s68, 31
	s_mov_b32 s81, 0xbfb8aa3b
	v_lshl_add_u64 v[2:3], s[12:13], 0, v[2:3]
	v_lshl_add_u64 v[2:3], s[68:69], 2, v[2:3]
	s_nop 0
	s_nop 0
	s_nop 0
	s_mov_b32 s65, 0x42ce8ed0
	s_mov_b32 s69, 0xc2b17218
	v_readlane_b32 s12, v254, 60
	s_add_i32 s28, s68, s12
	s_ashr_i32 s29, s28, 31
	s_mov_b64 s[90:91], s[84:85]
	s_mov_b64 s[84:85], s[16:17]
	s_mov_b64 s[76:77], s[40:41]
	s_mov_b64 s[40:41], s[44:45]
	s_mov_b64 s[44:45], s[38:39]
	s_mov_b64 s[38:39], s[72:73]
	s_mov_b64 s[72:73], s[10:11]
	s_mov_b64 s[10:11], s[6:7]
	s_mov_b64 s[6:7], s[4:5]
	s_mov_b64 s[4:5], s[58:59]
	s_mov_b64 s[58:59], s[56:57]
	s_mov_b64 s[56:57], s[66:67]
	s_mov_b64 s[66:67], s[18:19]
	s_mov_b64 s[34:35], s[86:87]
	s_mov_b64 s[86:87], s[24:25]
	s_mov_b32 s55, s20
	s_lshl_b64 s[28:29], s[28:29], 2
	s_waitcnt vmcnt(6) lgkmcnt(0)
	v_mov_b32_e32 v4, v92
	v_mov_b32_e32 v3, v93
	v_mul_f32_e32 v2, 0xbfb8aa3b, v4
	v_fma_f32 v5, v4, s81, -v2
	v_rndne_f32_e32 v6, v2
	v_fmac_f32_e32 v5, 0xb2a5705f, v4
	v_sub_f32_e32 v2, v2, v6
	v_add_f32_e32 v2, v2, v5
	v_exp_f32_e32 v2, v2
	v_cvt_i32_f32_e32 v5, v6
	v_cmp_nlt_f32_e32 vcc, s65, v4
	v_ldexp_f32 v2, v2, v5
	s_nop 0
	v_cndmask_b32_e32 v2, 0, v2, vcc
	v_cmp_ngt_f32_e32 vcc, s69, v4
	s_nop 1
	v_cndmask_b32_e32 v2, v219, v2, vcc
	s_mov_b64 vcc, s[14:15]
	v_readlane_b32 s12, v253, 42
	v_readlane_b32 s14, v253, 44
	v_readlane_b32 s15, v253, 45
	v_readlane_b32 s20, v253, 50
	v_readlane_b32 s21, v253, 51
	s_mov_b64 s[14:15], vcc
	s_add_u32 vcc_lo, s20, s28
	s_addc_u32 vcc_hi, s21, s29
	v_mov_b32_e32 v4, v94
	s_mov_b32 s20, s55
	s_mov_b32 s55, 0xb2a5705f
	v_readlane_b32 s18, v253, 48
	v_readlane_b32 s19, v253, 49
	s_add_u32 s28, s18, s28
	s_addc_u32 s29, s19, s29
	s_mov_b32 s21, 0x3fb8aa3b
	v_readlane_b32 s22, v253, 52
	s_mov_b32 s22, 0xc2ce8ed0
	s_mov_b32 s12, 0x42b17218
	v_readlane_b32 s26, v253, 56
	v_readlane_b32 s27, v253, 57
	v_readlane_b32 s26, v254, 61
	v_readlane_b32 s27, v254, 62
	v_add_f32_e32 v2, 1.0, v2
	v_readlane_b32 s16, v253, 46
	v_readlane_b32 s17, v253, 47
	v_readlane_b32 s24, v253, 54
	v_readlane_b32 s25, v253, 55
	v_readlane_b32 s13, v253, 43
	v_readlane_b32 s23, v253, 53
	s_mov_b64 s[24:25], s[86:87]
	s_mov_b64 s[86:87], s[34:35]
	s_mov_b64 s[34:35], 0x2000
	s_mov_b64 s[16:17], s[84:85]
	s_mov_b64 s[84:85], s[90:91]
	s_mov_b64 s[90:91], 0x200
	s_mov_b64 s[18:19], s[66:67]
	s_mov_b64 s[66:67], s[56:57]
	s_mov_b64 s[56:57], s[58:59]
	s_mov_b64 s[58:59], s[4:5]
	s_mov_b64 s[4:5], s[6:7]
	s_mov_b64 s[6:7], s[10:11]
	s_mov_b64 s[10:11], s[72:73]
	s_mov_b64 s[72:73], s[38:39]
	s_mov_b64 s[38:39], s[44:45]
	s_mov_b64 s[44:45], s[40:41]
	s_mov_b64 s[40:41], s[76:77]
	s_movk_i32 s76, 0x1800
	s_nop 0
	v_add_f32_e32 v3, v3, v4
	v_mul_f32_e64 v4, |v3|, s81
	v_fma_f32 v5, |v3|, s81, -v4
	v_rndne_f32_e32 v7, v4
	v_fma_f32 v5, |v3|, s55, v5
	v_sub_f32_e32 v4, v4, v7
	v_add_f32_e32 v4, v4, v5
	v_exp_f32_e32 v4, v4
	v_cvt_i32_f32_e32 v5, v7
	v_cmp_ngt_f32_e64 vcc, |v3|, s65
	v_max_f32_e32 v6, 0, v3
	s_mov_b32 s55, 0x3f2aaaab
	v_ldexp_f32 v4, v4, v5
	v_cndmask_b32_e32 v4, 0, v4, vcc
	v_cmp_nlt_f32_e64 vcc, |v3|, s69
	s_nop 1
	v_cndmask_b32_e32 v3, v219, v4, vcc
	v_add_f32_e32 v7, 1.0, v3
	v_add_f32_e32 v4, -1.0, v7
	v_sub_f32_e32 v5, v4, v7
	v_add_f32_e32 v5, 1.0, v5
	v_sub_f32_e32 v4, v3, v4
	v_add_f32_e32 v8, v4, v5
	v_frexp_mant_f32_e32 v4, v7
	v_cmp_gt_f32_e32 vcc, s55, v4
	v_cvt_f64_f32_e32 v[4:5], v7
	v_frexp_exp_i32_f64_e32 v4, v[4:5]
	v_subbrev_co_u32_e32 v4, vcc, 0, v4, vcc
	v_sub_u32_e32 v5, 0, v4
	v_ldexp_f32 v7, v7, v5
	v_ldexp_f32 v5, v8, v5
	v_add_f32_e32 v8, -1.0, v7
	v_add_f32_e32 v9, 1.0, v8
	v_sub_f32_e32 v9, v7, v9
	v_add_f32_e32 v9, v5, v9
	v_add_f32_e32 v10, v8, v9
	v_sub_f32_e32 v8, v8, v10
	v_add_f32_e32 v8, v9, v8
	v_add_f32_e32 v9, 1.0, v7
	v_add_f32_e32 v11, -1.0, v9
	v_sub_f32_e32 v7, v7, v11
	v_add_f32_e32 v5, v5, v7
	v_add_f32_e32 v7, v9, v5
	v_sub_f32_e32 v9, v9, v7
	v_add_f32_e32 v5, v5, v9
	v_rcp_f32_e32 v9, v7
	v_cvt_f32_i32_e32 v4, v4
	s_mov_b32 s55, 0x3f317218
	v_mul_f32_e32 v11, v10, v9
	v_mul_f32_e32 v12, v7, v11
	v_fma_f32 v13, v11, v7, -v12
	v_fmac_f32_e32 v13, v11, v5
	v_add_f32_e32 v14, v12, v13
	v_sub_f32_e32 v15, v10, v14
	v_sub_f32_e32 v10, v10, v15
	v_sub_f32_e32 v12, v14, v12
	v_sub_f32_e32 v10, v10, v14
	v_add_f32_e32 v8, v8, v10
	v_sub_f32_e32 v10, v12, v13
	v_add_f32_e32 v8, v10, v8
	v_add_f32_e32 v10, v15, v8
	v_mul_f32_e32 v12, v9, v10
	v_mul_f32_e32 v13, v7, v12
	v_fma_f32 v7, v12, v7, -v13
	v_fmac_f32_e32 v7, v12, v5
	v_sub_f32_e32 v5, v15, v10
	v_add_f32_e32 v5, v8, v5
	v_add_f32_e32 v8, v13, v7
	v_sub_f32_e32 v14, v10, v8
	v_sub_f32_e32 v10, v10, v14
	v_sub_f32_e32 v13, v8, v13
	v_sub_f32_e32 v8, v10, v8
	v_add_f32_e32 v5, v5, v8
	v_sub_f32_e32 v7, v13, v7
	v_add_f32_e32 v5, v7, v5
	v_add_f32_e32 v7, v11, v12
	v_add_f32_e32 v5, v14, v5
	v_sub_f32_e32 v8, v7, v11
	v_mul_f32_e32 v5, v9, v5
	v_sub_f32_e32 v8, v12, v8
	v_add_f32_e32 v5, v8, v5
	v_mul_f32_e32 v11, 0x3f317218, v4
	v_add_f32_e32 v8, v7, v5
	v_fma_f32 v12, v4, s55, -v11
	v_mul_f32_e32 v9, v8, v8
	v_mov_b32_e32 v10, 0x3ecc95a3
	v_fmac_f32_e32 v12, 0xb102e308, v4
	v_sub_f32_e32 v4, v8, v7
	v_fmamk_f32 v10, v9, 0x3e9b6dac, v10
	v_sub_f32_e32 v4, v5, v4
	v_add_f32_e32 v5, v11, v12
	v_fmaak_f32 v10, v9, v10, 0x3f2aaada
	v_sub_f32_e32 v7, v5, v11
	v_ldexp_f32 v11, v8, 1
	v_mul_f32_e32 v8, v8, v9
	v_mul_f32_e32 v8, v8, v10
	v_add_f32_e32 v9, v11, v8
	v_sub_f32_e32 v10, v9, v11
	v_ldexp_f32 v4, v4, 1
	v_sub_f32_e32 v8, v8, v10
	v_add_f32_e32 v4, v4, v8
	v_add_f32_e32 v8, v9, v4
	v_sub_f32_e32 v9, v8, v9
	v_sub_f32_e32 v4, v4, v9
	v_add_f32_e32 v9, v5, v8
	v_sub_f32_e32 v10, v9, v5
	v_sub_f32_e32 v11, v9, v10
	v_sub_f32_e32 v7, v12, v7
	v_sub_f32_e32 v5, v5, v11
	v_sub_f32_e32 v8, v8, v10
	v_add_f32_e32 v5, v8, v5
	v_add_f32_e32 v8, v7, v4
	v_sub_f32_e32 v10, v8, v7
	v_sub_f32_e32 v11, v8, v10
	v_sub_f32_e32 v7, v7, v11
	v_sub_f32_e32 v4, v4, v10
	v_add_f32_e32 v5, v8, v5
	v_add_f32_e32 v4, v4, v7
	v_add_f32_e32 v7, v9, v5
	v_sub_f32_e32 v8, v7, v9
	v_sub_f32_e32 v5, v5, v8
	v_add_f32_e32 v4, v4, v5
	s_mov_b32 s55, 0x7f800000
	v_add_f32_e32 v4, v7, v4
	v_cmp_neq_f32_e32 vcc, s55, v3
	s_mov_b32 s55, 0x33800000
	s_nop 0
	v_cndmask_b32_e32 v4, v219, v4, vcc
	v_cmp_lt_f32_e64 vcc, |v3|, s55
	s_movk_i32 s55, 0xf000
	s_nop 0
	v_cndmask_b32_e32 v3, v4, v3, vcc
	v_mov_b32_e32 v4, v95
	v_add_f32_e32 v3, v6, v3
	s_nop 0
	v_mul_f32_e32 v5, 0x3fb8aa3b, v4
	v_fma_f32 v6, v4, s21, -v5
	v_rndne_f32_e32 v7, v5
	v_fmac_f32_e32 v6, 0x32a5705f, v4
	v_sub_f32_e32 v5, v5, v7
	v_add_f32_e32 v5, v5, v6
	v_exp_f32_e32 v5, v5
	v_cvt_i32_f32_e32 v6, v7
	v_cmp_ngt_f32_e32 vcc, s22, v4
	v_add_u32_e32 v7, -1, v218
	v_ldexp_f32 v5, v5, v6
	v_cndmask_b32_e32 v5, 0, v5, vcc
	v_cmp_nlt_f32_e32 vcc, s12, v4
	s_nop 1
	v_cndmask_b32_e32 v4, v219, v5, vcc
	v_and_b32_e32 v5, 64, v218
	v_cmp_lt_i32_e32 vcc, v7, v5
	v_mul_f32_e64 v6, v3, -v4
	s_nop 0
	v_cndmask_b32_e32 v7, v7, v218, vcc
	v_lshlrev_b32_e32 v7, 2, v7
	ds_bpermute_b32 v7, v7, v6
	s_waitcnt lgkmcnt(0)
	v_fma_f32 v3, v3, -v4, v7
	v_add_u32_e32 v4, -2, v218
	v_cmp_lt_i32_e32 vcc, v4, v5
	v_cndmask_b32_e64 v3, v3, v6, s[26:27]
	v_readlane_b32 s26, v254, 63
	v_cndmask_b32_e32 v4, v4, v218, vcc
	v_lshlrev_b32_e32 v4, 2, v4
	ds_bpermute_b32 v4, v4, v3
	v_readlane_b32 s27, v255, 0
	s_waitcnt lgkmcnt(0)
	v_add_f32_e32 v4, v3, v4
	v_cndmask_b32_e64 v3, v4, v3, s[26:27]
	v_add_u32_e32 v4, -4, v218
	v_cmp_lt_i32_e32 vcc, v4, v5
	v_readlane_b32 s26, v255, 1
	v_readlane_b32 s27, v255, 2
	v_cndmask_b32_e32 v4, v4, v218, vcc
	v_lshlrev_b32_e32 v4, 2, v4
	ds_bpermute_b32 v4, v4, v3
	s_waitcnt lgkmcnt(0)
	v_add_f32_e32 v4, v3, v4
	v_cndmask_b32_e64 v3, v4, v3, s[26:27]
	v_add_u32_e32 v4, -8, v218
	v_cmp_lt_i32_e32 vcc, v4, v5
	v_readlane_b32 s26, v255, 3
	v_readlane_b32 s27, v255, 4
	v_cndmask_b32_e32 v4, v4, v218, vcc
	v_lshlrev_b32_e32 v4, 2, v4
	ds_bpermute_b32 v4, v4, v3
	s_waitcnt lgkmcnt(0)
	v_add_f32_e32 v4, v3, v4
	v_cndmask_b32_e64 v3, v4, v3, s[26:27]
	v_add_u32_e32 v4, -16, v218
	v_cmp_lt_i32_e32 vcc, v4, v5
	v_readlane_b32 s26, v255, 5
	v_readlane_b32 s27, v255, 6
	v_cndmask_b32_e32 v4, v4, v218, vcc
	v_lshlrev_b32_e32 v4, 2, v4
	ds_bpermute_b32 v4, v4, v3
	s_waitcnt lgkmcnt(0)
	v_add_f32_e32 v4, v3, v4
	v_cndmask_b32_e64 v3, v4, v3, s[26:27]
	v_subrev_u32_e32 v4, 32, v218
	v_cmp_lt_i32_e32 vcc, v4, v5
	v_readlane_b32 s26, v255, 7
	v_readlane_b32 s27, v255, 8
	v_cndmask_b32_e32 v4, v4, v218, vcc
	v_lshlrev_b32_e32 v4, 2, v4
	ds_bpermute_b32 v4, v4, v3
	s_waitcnt lgkmcnt(0)
	v_add_f32_e32 v4, v3, v4
	v_cndmask_b32_e64 v3, v4, v3, s[26:27]
	v_div_scale_f32 v4, s[28:29], v2, v2, 1.0
	v_rcp_f32_e32 v5, v4
	v_readlane_b32 s26, v255, 51
	v_readlane_b32 s27, v255, 52
	v_fma_f32 v6, -v4, v5, 1.0
	v_fmac_f32_e32 v5, v6, v5
	v_div_scale_f32 v6, vcc, 1.0, v2, 1.0
	v_mul_f32_e32 v7, v6, v5
	v_fma_f32 v8, -v4, v7, v6
	v_fmac_f32_e32 v7, v8, v5
	v_fma_f32 v4, -v4, v7, v6
	v_div_fmas_f32 v4, v4, v5, v7
	v_div_fixup_f32 v2, v4, v2, 1.0
	v_mul_f32_e32 v4, 0x3fb8aa3b, v3
	v_fma_f32 v5, v3, s21, -v4
	v_rndne_f32_e32 v6, v4
	v_fmac_f32_e32 v5, 0x32a5705f, v3
	v_sub_f32_e32 v4, v4, v6
	v_add_f32_e32 v4, v4, v5
	v_exp_f32_e32 v4, v4
	v_cvt_i32_f32_e32 v5, v6
	v_cmp_ngt_f32_e32 vcc, s22, v3
	v_ldexp_f32 v4, v4, v5
	s_nop 0
	v_cndmask_b32_e32 v4, 0, v4, vcc
	v_cmp_nlt_f32_e32 vcc, s12, v3
	v_lshl_add_u32 v5, v160, 2, v239
	ds_write2st64_b32 v5, v2, v3 offset1:1
	v_cndmask_b32_e32 v4, v219, v4, vcc
	v_mul_f32_e32 v2, v2, v4
	ds_write2st64_b32 v5, v4, v2 offset0:2 offset1:5
